# mixer A dilated groups: K/V^T tiles loaded as whole 128-byte lines (8 rows x 8 lanes per load) and re-shaped into MFMA fragment layout through a per-wave LDS buffer, instead of 16-row half-line gather
# speedup vs baseline: 1.0374x; 1.0141x over previous
.LBB0_617:
	v_lshrrev_b32_e32 v210, 3, v111
	v_lshl_add_u32 v210, v112, 1, v210
	v_and_b32_e32 v211, 7, v111
	v_lshlrev_b32_e32 v208, 4, v211
	v_mov_b32_e32 v209, v137
	v_lshlrev_b32_e32 v212, 3, v211
	v_mov_b32_e32 v213, v137
	v_mov_b32_e32 v214, 0x10000
	v_mov_b32_e32 v215, v137
	v_mov_b32_e32 v232, 0x1000
	v_mov_b32_e32 v233, v137
	v_readlane_b32 s100, v255, 8
	s_nop 0
	s_mul_i32 s100, s100, 0x280
	s_add_i32 s100, s100, 0x4000
	v_mul_u32_u24_e32 v234, 0xa0, v210
	v_lshl_add_u32 v234, v211, 4, v234
	v_add_u32_e32 v234, s100, v234
	v_mul_u32_u24_e32 v235, 0xa0, v111
	v_lshl_add_u32 v235, v112, 4, v235
	v_add_u32_e32 v235, s100, v235
	s_ashr_i32 s6, s45, 2
	s_max_i32 s6, s6, 0x80
	s_add_i32 s56, s45, 0xf0
	s_addk_i32 s6, 0xff80
	v_lshlrev_b32_e32 v16, 12, v210
	s_ashr_i32 s57, s56, 8
	s_lshr_b32 s58, s6, 6
	v_lshlrev_b64 v[92:93], 1, v[90:91]
	s_mov_b64 s[78:79], 0x40000
	s_movk_i32 s84, 0x121
	s_cmp_gt_i32 s58, s57
	v_lshl_add_u64 v[98:99], v[32:33], 0, v[92:93]
	v_lshlrev_b32_e32 v96, 1, v16
	v_lshlrev_b32_e32 v94, 13, v210
	s_cbranch_scc1 .LBB0_622
	v_add_co_u32_e32 v20, vcc, 0xc00000, v98
	v_readlane_b32 s7, v255, 47
	s_nop 0
	v_addc_co_u32_e32 v21, vcc, 0, v99, vcc
	global_load_dwordx4 v[16:19], v[20:21], off
	s_nop 0
	global_load_dwordx4 v[20:23], v[20:21], off offset:64
	v_lshl_or_b32 v136, v210, 9, s7
	v_readlane_b32 s10, v255, 48
	s_waitcnt vmcnt(0)
	v_lshl_add_u64 v[24:25], s[38:39], 0, v[136:137]
	s_mov_b64 s[8:9], 0xc00000
	v_mov_b32_e32 v97, v137
	v_readlane_b32 s11, v255, 49
	v_lshl_add_u64 v[100:101], v[24:25], 0, s[8:9]
	v_lshl_add_u64 v[24:25], s[52:53], 0, v[96:97]
	s_mov_b32 s11, s93
	s_mov_b32 s12, s10
	v_writelane_b32 v255, s12, 48
	v_lshl_add_u64 v[24:25], v[24:25], 0, s[10:11]
	v_lshl_add_u64 v[24:25], v[24:25], 0, v[208:209]
	v_writelane_b32 v255, s13, 49
	s_mov_b32 s41, s93
	s_lshr_b32 s92, s6, 6
	v_lshl_add_u64 v[102:103], v[24:25], 0, s[8:9]
	s_and_b32 s54, s6, 0xffffffc0
	s_lshl_b64 s[8:9], s[40:41], 19
	s_lshl_b64 s[6:7], s[92:93], 7
	v_readlane_b32 s10, v255, 44
	s_add_u32 s6, s10, s6
	v_readlane_b32 s10, v255, 45
	s_addc_u32 s7, s10, s7
	s_add_u32 s6, s6, s8
	v_mov_b32_e32 v95, v137
	s_addc_u32 s7, s7, s9
	v_lshl_add_u64 v[104:105], s[6:7], 0, v[94:95]
	s_lshl_b64 s[6:7], s[92:93], 15
	s_add_u32 s6, s8, s6
	v_ashrrev_i32_e32 v26, 2, v88
	v_lshlrev_b32_e32 v24, 2, v112
	s_addc_u32 s7, s9, s7
	v_add_u32_e32 v25, s54, v24
	v_sub_u32_e32 v24, v26, v24
	s_add_u32 s6, s74, s6
	v_subrev_u32_e32 v24, s54, v24
	s_addc_u32 s7, s75, s7
	v_sub_u32_e32 v97, v25, v26
	v_add_u32_e32 v116, 0xffffff9d, v24
	v_lshl_add_u64 v[106:107], s[6:7], 0, v[136:137]
	s_mov_b32 s92, s58
	s_branch .LBB0_620
.LBB0_619:
	v_lshl_add_u64 v[48:49], v[104:105], 0, v[208:209]
	v_add_co_u32_e32 v28, vcc, 0xc460000, v48
	v_lshl_add_u64 v[80:81], v[106:107], 0, v[208:209]
	s_nop 0
	v_addc_co_u32_e32 v29, vcc, 0, v49, vcc
	v_add_co_u32_e32 v36, vcc, 0xc440000, v48
	v_lshl_add_u64 v[236:237], v[28:29], 0, v[214:215]
	global_load_dwordx4 v[24:27], v[236:237], off offset:128
	s_nop 0
	global_load_dwordx4 v[28:31], v[28:29], off offset:128
	v_addc_co_u32_e32 v37, vcc, 0, v49, vcc
	v_add_co_u32_e32 v44, vcc, 0xc420000, v48
	v_lshl_add_u64 v[236:237], v[36:37], 0, v[214:215]
	global_load_dwordx4 v[32:35], v[236:237], off offset:128
	s_nop 0
	global_load_dwordx4 v[36:39], v[36:37], off offset:128
	v_addc_co_u32_e32 v45, vcc, 0, v49, vcc
	v_add_co_u32_e32 v52, vcc, 0xc400000, v48
	v_lshl_add_u64 v[236:237], v[44:45], 0, v[214:215]
	global_load_dwordx4 v[40:43], v[236:237], off offset:128
	s_nop 0
	global_load_dwordx4 v[44:47], v[44:45], off offset:128
	v_addc_co_u32_e32 v53, vcc, 0, v49, vcc
	v_add_co_u32_e32 v60, vcc, 0xa00e000, v80
	v_lshl_add_u64 v[236:237], v[52:53], 0, v[214:215]
	global_load_dwordx4 v[48:51], v[236:237], off offset:128
	s_nop 0
	global_load_dwordx4 v[52:55], v[52:53], off offset:128
	v_addc_co_u32_e32 v61, vcc, 0, v81, vcc
	v_add_co_u32_e32 v64, vcc, 0xa00c000, v80
	v_lshl_add_u64 v[236:237], v[60:61], 0, v[232:233]
	global_load_dwordx4 v[56:59], v[236:237], off
	global_load_dwordx4 v[68:71], v[60:61], off
	v_addc_co_u32_e32 v65, vcc, 0, v81, vcc
	v_add_co_u32_e32 v76, vcc, 0xa00a000, v80
	v_lshl_add_u64 v[236:237], v[64:65], 0, v[232:233]
	global_load_dwordx4 v[60:63], v[236:237], off
	global_load_dwordx4 v[72:75], v[64:65], off
	v_addc_co_u32_e32 v77, vcc, 0, v81, vcc
	v_add_co_u32_e32 v84, vcc, 0xa008000, v80
	v_lshl_add_u64 v[236:237], v[76:77], 0, v[232:233]
	global_load_dwordx4 v[64:67], v[236:237], off
	s_nop 0
	global_load_dwordx4 v[76:79], v[76:77], off
	v_addc_co_u32_e32 v85, vcc, 0, v81, vcc
	v_lshl_add_u64 v[236:237], v[84:85], 0, v[232:233]
	global_load_dwordx4 v[80:83], v[236:237], off
	s_nop 0
	global_load_dwordx4 v[84:87], v[84:85], off
	v_add_u32_e32 v95, 35, v116
	v_cmp_gt_u32_e64 s[22:23], s47, v95
	v_add_u32_e32 v95, 64, v97
	v_add_u32_e32 v122, 0xffffff90, v116
	v_add_u32_e32 v123, 0xffffff8f, v116
	v_cmp_gt_u32_e64 s[20:21], s88, v95
	v_add_u32_e32 v118, 0xffffffa0, v116
	v_add_u32_e32 v119, 0xffffff9f, v116
	v_cmp_gt_u32_e64 s[8:9], s88, v122
	v_cmp_gt_u32_e32 vcc, s88, v123
	v_cndmask_b32_e64 v95, 2, 0, s[20:21]
	v_cmp_gt_u32_e64 s[16:17], s88, v118
	v_cmp_gt_u32_e64 s[18:19], s88, v119
	v_cndmask_b32_e64 v122, 64, 0, s[8:9]
	v_cndmask_b32_e64 v123, v244, 0, vcc
	v_cndmask_b32_e64 v118, 4, 0, s[16:17]
	v_cndmask_b32_e64 v119, 8, 0, s[18:19]
	v_add_u32_e32 v120, 0xffffff92, v116
	v_add_u32_e32 v121, 0xffffff91, v116
	v_or3_b32 v95, v122, v123, v95
	v_cmp_gt_u32_e64 s[6:7], s88, v120
	v_cmp_gt_u32_e64 s[10:11], s88, v121
	v_or3_b32 v95, v118, v119, v95
	v_add_u32_e32 v118, 3, v116
	v_add_u32_e32 v119, 2, v116
	v_cndmask_b32_e64 v120, 16, 0, s[6:7]
	v_cndmask_b32_e64 v121, 32, 0, s[10:11]
	v_cmp_gt_u32_e64 s[14:15], s47, v118
	v_cmp_gt_u32_e64 s[12:13], s47, v119
	v_or3_b32 v95, v120, v121, v95
	v_cndmask_b32_e64 v118, 0, v245, s[14:15]
	v_cndmask_b32_e64 v119, 0, v240, s[12:13]
	v_or3_b32 v95, v118, v95, v119
	v_add_u32_e32 v118, 1, v116
	v_cmp_gt_u32_e64 s[24:25], s47, v118
	v_add_u32_e32 v120, -13, v116
	v_add_u32_e32 v121, -14, v116
	v_cndmask_b32_e64 v118, 0, v246, s[24:25]
	v_cmp_gt_u32_e64 s[24:25], s47, v116
	v_add_u32_e32 v122, -15, v116
	v_add_u32_e32 v123, -16, v116
	v_cndmask_b32_e64 v119, 0, v247, s[24:25]
	v_cmp_gt_u32_e64 s[24:25], s47, v120
	v_or_b32_e32 v118, v118, v119
	v_or_b32_e32 v119, v118, v95
	v_cndmask_b32_e64 v120, 0, v248, s[24:25]
	v_cmp_gt_u32_e64 s[24:25], s47, v121
	s_add_i32 s58, s58, 2
	s_min_i32 s92, s58, s57
	s_waitcnt vmcnt(0) lgkmcnt(0)
	ds_write_b128 v234, v[68:71]
	ds_write_b128 v234, v[56:59] offset:1280
	ds_write_b128 v234, v[72:75] offset:2560
	ds_write_b128 v234, v[60:63] offset:3840
	ds_write_b128 v234, v[76:79] offset:5120
	ds_write_b128 v234, v[64:67] offset:6400
	ds_write_b128 v234, v[84:87] offset:7680
	ds_write_b128 v234, v[80:83] offset:8960
	ds_read_b128 v[68:71], v235
	ds_read_b128 v[56:59], v235 offset:64
	ds_read_b128 v[72:75], v235 offset:2560
	ds_read_b128 v[60:63], v235 offset:2624
	ds_read_b128 v[76:79], v235 offset:5120
	ds_read_b128 v[64:67], v235 offset:5184
	ds_read_b128 v[84:87], v235 offset:7680
	ds_read_b128 v[80:83], v235 offset:7744
	ds_write_b128 v234, v[28:31]
	ds_write_b128 v234, v[24:27] offset:1280
	ds_write_b128 v234, v[36:39] offset:2560
	ds_write_b128 v234, v[32:35] offset:3840
	ds_write_b128 v234, v[44:47] offset:5120
	ds_write_b128 v234, v[40:43] offset:6400
	ds_write_b128 v234, v[52:55] offset:7680
	ds_write_b128 v234, v[48:51] offset:8960
	ds_read_b128 v[28:31], v235
	ds_read_b128 v[24:27], v235 offset:64
	ds_read_b128 v[36:39], v235 offset:2560
	ds_read_b128 v[32:35], v235 offset:2624
	ds_read_b128 v[44:47], v235 offset:5120
	ds_read_b128 v[40:43], v235 offset:5184
	ds_read_b128 v[52:55], v235 offset:7680
	ds_read_b128 v[48:51], v235 offset:7744
	s_waitcnt lgkmcnt(0)
	v_mfma_f32_16x16x32_bf16 v[68:71], v[68:71], v[16:19], 0
	v_cndmask_b32_e64 v121, 0, v249, s[24:25]
	v_cmp_gt_u32_e64 s[24:25], s47, v122
	v_or_b32_e32 v120, v120, v121
	v_mfma_f32_16x16x32_bf16 v[84:87], v[84:87], v[16:19], 0
	v_cndmask_b32_e64 v122, 0, v250, s[24:25]
	v_cmp_gt_u32_e64 s[24:25], s47, v123
	v_or_b32_e32 v121, v120, v119
	v_mfma_f32_16x16x32_bf16 v[76:79], v[76:79], v[16:19], 0
	v_cndmask_b32_e64 v123, 0, v251, s[24:25]
	v_or_b32_e32 v122, v122, v123
	s_lshl_b32 s54, s92, 6
	v_mfma_f32_16x16x32_bf16 v[72:75], v[72:75], v[16:19], 0
	s_cmp_gt_i32 s58, s57
	v_add_u32_e32 v97, 0x80, v97
	v_add_u32_e32 v116, 0xffffff80, v116
	v_mfma_f32_16x16x32_bf16 v[80:83], v[80:83], v[20:23], v[84:87]
	v_mfma_f32_16x16x32_bf16 v[64:67], v[64:67], v[20:23], v[76:79]
	v_mfma_f32_16x16x32_bf16 v[60:63], v[60:63], v[20:23], v[72:75]
	v_mfma_f32_16x16x32_bf16 v[56:59], v[56:59], v[20:23], v[68:71]
	s_nop 4
	v_mul_f32_e32 v72, 0x3e38aa3b, v83
	v_bitop3_b32 v73, v118, s95, v95 bitop3:0xc8
	v_cndmask_b32_e64 v72, v72, v241, s[18:19]
	v_mul_f32_e32 v68, 0x3e38aa3b, v80
	v_mul_f32_e32 v69, 0x3e38aa3b, v81
	v_cndmask_b32_e64 v68, v241, v68, s[22:23]
	v_cndmask_b32_e64 v69, v69, v241, s[20:21]
	v_mul_f32_e32 v71, 0x3e38aa3b, v82
	v_max3_f32 v70, v68, s71, v69
	v_cndmask_b32_e64 v71, v71, v241, s[16:17]
	v_mul_f32_e32 v64, 0x3e38aa3b, v64
	v_mul_f32_e32 v65, 0x3e38aa3b, v65
	v_cmp_eq_u32_e64 s[36:37], 0, v73
	v_bitop3_b32 v73, v118, s48, v95 bitop3:0xc8
	v_max3_f32 v70, v70, v71, v72
	v_cndmask_b32_e64 v64, v64, v241, s[6:7]
	v_cndmask_b32_e64 v65, v65, v241, s[10:11]
	v_mul_f32_e32 v66, 0x3e38aa3b, v66
	v_mul_f32_e32 v67, 0x3e38aa3b, v67
	v_cmp_eq_u32_e64 s[26:27], 0, v73
	v_bitop3_b32 v73, v120, s90, v119 bitop3:0xc8
	v_max3_f32 v70, v70, v64, v65
	v_cndmask_b32_e64 v66, v66, v241, s[8:9]
	v_cndmask_b32_e32 v67, v67, v241, vcc
	v_mul_f32_e32 v60, 0x3e38aa3b, v60
	v_mul_f32_e32 v61, 0x3e38aa3b, v61
	v_cmp_eq_u32_e64 s[34:35], 0, v73
	v_bitop3_b32 v73, v120, s83, v119 bitop3:0xc8
	v_max3_f32 v70, v70, v66, v67
	v_cndmask_b32_e64 v60, v241, v60, s[14:15]
	v_cndmask_b32_e64 v61, v241, v61, s[12:13]
	v_mul_f32_e32 v62, 0x3e38aa3b, v62
	v_mul_f32_e32 v63, 0x3e38aa3b, v63
	v_cmp_eq_u32_e64 s[30:31], 0, v73
	v_bitop3_b32 v73, v122, s50, v121 bitop3:0xc8
	v_max3_f32 v70, v70, v60, v61
	v_cndmask_b32_e64 v62, v62, v241, s[36:37]
	v_cndmask_b32_e64 v63, v63, v241, s[26:27]
	v_mul_f32_e32 v56, 0x3e38aa3b, v56
	v_mul_f32_e32 v57, 0x3e38aa3b, v57
	v_cmp_eq_u32_e64 s[28:29], 0, v73
	v_bitop3_b32 v73, v122, s82, v121 bitop3:0xc8
	v_max3_f32 v70, v70, v62, v63
	v_cndmask_b32_e64 v56, v56, v241, s[34:35]
	v_cndmask_b32_e64 v57, v57, v241, s[30:31]
	v_mul_f32_e32 v58, 0x3e38aa3b, v58
	v_cmp_eq_u32_e64 s[24:25], 0, v73
	v_mul_f32_e32 v59, 0x3e38aa3b, v59
	v_max3_f32 v70, v70, v56, v57
	v_cndmask_b32_e64 v58, v58, v241, s[28:29]
	v_cndmask_b32_e64 v59, v59, v241, s[24:25]
	v_max3_f32 v70, v70, v58, v59
	ds_bpermute_b32 v73, v109, v70
	s_waitcnt lgkmcnt(0)
	v_max_f32_e32 v73, v73, v73
	v_max_f32_e32 v70, v70, v73
	ds_bpermute_b32 v73, v108, v70
	s_waitcnt lgkmcnt(0)
	v_max3_f32 v118, v117, v70, v73
	v_sub_f32_e32 v68, v68, v118
	v_exp_f32_e32 v68, v68
	v_sub_f32_e32 v69, v69, v118
	v_exp_f32_e32 v69, v69
	v_sub_f32_e32 v71, v71, v118
	v_exp_f32_e32 v71, v71
	v_sub_f32_e32 v72, v72, v118
	v_exp_f32_e32 v72, v72
	v_sub_f32_e32 v64, v64, v118
	v_cndmask_b32_e64 v68, 0, v68, s[22:23]
	v_exp_f32_e32 v64, v64
	v_sub_f32_e32 v65, v65, v118
	v_add_f32_e32 v73, 0, v68
	v_cndmask_b32_e64 v69, v69, 0, s[20:21]
	v_exp_f32_e32 v65, v65
	v_sub_f32_e32 v66, v66, v118
	v_sub_f32_e32 v57, v57, v118
	v_add_f32_e32 v73, v69, v73
	v_cndmask_b32_e64 v71, v71, 0, s[16:17]
	v_exp_f32_e32 v66, v66
	v_sub_f32_e32 v67, v67, v118
	v_exp_f32_e32 v57, v57
	v_add_f32_e32 v73, v71, v73
	v_cndmask_b32_e64 v72, v72, 0, s[18:19]
	v_exp_f32_e32 v67, v67
	v_sub_f32_e32 v60, v60, v118
	v_add_f32_e32 v73, v72, v73
	v_cndmask_b32_e64 v74, v64, 0, s[6:7]
	v_exp_f32_e32 v60, v60
	v_sub_f32_e32 v61, v61, v118
	v_add_f32_e32 v64, v74, v73
	v_cndmask_b32_e64 v65, v65, 0, s[10:11]
	v_exp_f32_e32 v61, v61
	v_sub_f32_e32 v62, v62, v118
	v_add_f32_e32 v64, v65, v64
	v_cndmask_b32_e64 v66, v66, 0, s[8:9]
	v_exp_f32_e32 v62, v62
	v_sub_f32_e32 v63, v63, v118
	v_cndmask_b32_e64 v75, v57, 0, s[30:31]
	v_sub_f32_e32 v57, v58, v118
	v_add_f32_e32 v64, v66, v64
	v_cndmask_b32_e64 v67, v67, 0, vcc
	v_exp_f32_e32 v63, v63
	v_sub_f32_e32 v56, v56, v118
	v_exp_f32_e32 v57, v57
	v_add_f32_e32 v64, v67, v64
	v_cndmask_b32_e64 v60, 0, v60, s[14:15]
	v_exp_f32_e32 v56, v56
	v_add_f32_e32 v64, v60, v64
	v_cndmask_b32_e64 v61, 0, v61, s[12:13]
	v_add_f32_e32 v64, v61, v64
	v_cndmask_b32_e64 v62, v62, 0, s[36:37]
	v_add_f32_e32 v64, v62, v64
	v_cndmask_b32_e64 v63, v63, 0, s[26:27]
	v_cndmask_b32_e64 v76, v57, 0, s[28:29]
	v_sub_f32_e32 v57, v59, v118
	v_sub_f32_e32 v70, v117, v118
	v_add_f32_e32 v64, v63, v64
	v_cndmask_b32_e64 v73, v56, 0, s[34:35]
	v_exp_f32_e32 v57, v57
	v_add_f32_e32 v56, v73, v64
	v_exp_f32_e32 v64, v70
	v_add_f32_e32 v56, v75, v56
	v_add_f32_e32 v56, v76, v56
	v_cndmask_b32_e64 v77, v57, 0, s[24:25]
	v_add_f32_e32 v119, v77, v56
	v_cvt_pk_bf16_f32 v56, v68, v69
	v_cvt_pk_bf16_f32 v57, v71, v72
	v_cvt_pk_bf16_f32 v58, v74, v65
	v_cvt_pk_bf16_f32 v59, v66, v67
	v_pk_mul_f32 v[10:11], v[10:11], v[64:65] op_sel_hi:[1,0]
	v_pk_mul_f32 v[8:9], v[8:9], v[64:65] op_sel_hi:[1,0]
	v_pk_mul_f32 v[14:15], v[14:15], v[64:65] op_sel_hi:[1,0]
	v_pk_mul_f32 v[12:13], v[12:13], v[64:65] op_sel_hi:[1,0]
	v_pk_mul_f32 v[6:7], v[6:7], v[64:65] op_sel_hi:[1,0]
	v_pk_mul_f32 v[4:5], v[4:5], v[64:65] op_sel_hi:[1,0]
	v_pk_mul_f32 v[2:3], v[2:3], v[64:65] op_sel_hi:[1,0]
	v_pk_mul_f32 v[0:1], v[0:1], v[64:65] op_sel_hi:[1,0]
	v_mfma_f32_16x16x32_bf16 v[8:11], v[52:55], v[56:59], v[8:11]
	v_cvt_pk_bf16_f32 v60, v60, v61
	v_cvt_pk_bf16_f32 v61, v62, v63
	v_cvt_pk_bf16_f32 v62, v73, v75
	v_mfma_f32_16x16x32_bf16 v[12:15], v[44:47], v[56:59], v[12:15]
	v_cvt_pk_bf16_f32 v63, v76, v77
	s_mov_b64 s[6:7], 0x100
	v_fmac_f32_e32 v119, v114, v64
	v_mfma_f32_16x16x32_bf16 v[4:7], v[36:39], v[56:59], v[4:7]
	v_lshl_add_u64 v[104:105], v[104:105], 0, s[6:7]
	s_mov_b64 s[6:7], 0x10000
	v_lshl_add_u64 v[106:107], v[106:107], 0, s[6:7]
	v_mfma_f32_16x16x32_bf16 v[0:3], v[28:31], v[56:59], v[0:3]
	s_cselect_b64 s[6:7], -1, 0
	v_mov_b32_e32 v117, v118
	v_mov_b32_e32 v114, v119
	v_mfma_f32_16x16x32_bf16 v[8:11], v[48:51], v[60:63], v[8:11]
	v_mfma_f32_16x16x32_bf16 v[12:15], v[40:43], v[60:63], v[12:15]
	v_mfma_f32_16x16x32_bf16 v[4:7], v[32:35], v[60:63], v[4:7]
	v_mfma_f32_16x16x32_bf16 v[0:3], v[24:27], v[60:63], v[0:3]
	s_andn2_b64 vcc, exec, s[6:7]
	s_cbranch_vccz .LBB0_623
.LBB0_620:
	s_lshl_b64 s[6:7], s[92:93], 15
	v_lshl_add_u64 v[24:25], v[100:101], 0, s[6:7]
	v_lshl_add_u64 v[24:25], v[212:213], 1, v[24:25]
	v_add_co_u32_e32 v26, vcc, s50, v24
	s_movk_i32 s6, 0x6000
	s_nop 0
	v_addc_co_u32_e32 v27, vcc, 0, v25, vcc
	v_lshl_add_u64 v[236:237], v[26:27], 0, v[232:233]
	global_load_dwordx4 v[56:59], v[236:237], off
	global_load_dwordx4 v[72:75], v[26:27], off
	v_add_co_u32_e32 v26, vcc, s83, v24
	s_mov_b32 s55, s93
	s_nop 0
	v_addc_co_u32_e32 v27, vcc, 0, v25, vcc
	v_lshl_add_u64 v[236:237], v[26:27], 0, v[232:233]
	global_load_dwordx4 v[60:63], v[236:237], off
	global_load_dwordx4 v[76:79], v[26:27], off
	v_lshl_add_u64 v[236:237], v[24:25], 0, v[232:233]
	global_load_dwordx4 v[64:67], v[236:237], off
	global_load_dwordx4 v[80:83], v[24:25], off
	v_add_co_u32_e32 v24, vcc, s6, v24
	s_mov_b32 s6, 0x40000
	s_nop 0
	v_addc_co_u32_e32 v25, vcc, 0, v25, vcc
	global_load_dwordx4 v[120:123], v[24:25], off
	v_lshl_add_u64 v[236:237], v[24:25], 0, v[232:233]
	global_load_dwordx4 v[68:71], v[236:237], off
	v_lshl_add_u64 v[24:25], s[54:55], 1, v[102:103]
	v_add_co_u32_e32 v26, vcc, s0, v24
	global_load_dwordx4 v[52:55], v[24:25], off
	v_lshl_add_u64 v[236:237], v[24:25], 0, v[214:215]
	global_load_dwordx4 v[48:51], v[236:237], off
	v_addc_co_u32_e32 v27, vcc, 0, v25, vcc
	global_load_dwordx4 v[44:47], v[26:27], off
	v_lshl_add_u64 v[236:237], v[26:27], 0, v[214:215]
	global_load_dwordx4 v[40:43], v[236:237], off
	v_add_co_u32_e32 v26, vcc, s6, v24
	v_add_u32_e32 v95, 0x63, v116
	s_nop 0
	v_addc_co_u32_e32 v27, vcc, 0, v25, vcc
	v_add_co_u32_e32 v28, vcc, s76, v24
	global_load_dwordx4 v[36:39], v[26:27], off
	v_lshl_add_u64 v[236:237], v[26:27], 0, v[214:215]
	global_load_dwordx4 v[32:35], v[236:237], off
	v_addc_co_u32_e32 v29, vcc, 0, v25, vcc
	global_load_dwordx4 v[24:27], v[28:29], off
	s_nop 0
	v_lshl_add_u64 v[236:237], v[28:29], 0, v[214:215]
	global_load_dwordx4 v[28:31], v[236:237], off
	v_cmp_gt_u32_e64 s[20:21], s88, v97
	v_add_u32_e32 v114, 0x61, v116
	v_add_u32_e32 v117, 0x60, v116
	v_cmp_gt_u32_e64 s[22:23], s47, v95
	v_cndmask_b32_e64 v95, 2, 0, s[20:21]
	v_cmp_lt_u32_e64 s[12:13], s49, v114
	v_cmp_lt_u32_e64 s[18:19], s49, v117
	s_cmp_ge_i32 s58, s57
	v_cndmask_b32_e64 v114, 4, 0, s[12:13]
	v_cndmask_b32_e64 v117, 8, 0, s[18:19]
	s_waitcnt vmcnt(0) lgkmcnt(0)
	ds_write_b128 v234, v[72:75]
	ds_write_b128 v234, v[56:59] offset:1280
	ds_write_b128 v234, v[76:79] offset:2560
	ds_write_b128 v234, v[60:63] offset:3840
	ds_write_b128 v234, v[80:83] offset:5120
	ds_write_b128 v234, v[64:67] offset:6400
	ds_write_b128 v234, v[120:123] offset:7680
	ds_write_b128 v234, v[68:71] offset:8960
	ds_read_b128 v[72:75], v235
	ds_read_b128 v[56:59], v235 offset:64
	ds_read_b128 v[76:79], v235 offset:2560
	ds_read_b128 v[60:63], v235 offset:2624
	ds_read_b128 v[80:83], v235 offset:5120
	ds_read_b128 v[64:67], v235 offset:5184
	ds_read_b128 v[120:123], v235 offset:7680
	ds_read_b128 v[68:71], v235 offset:7744
	ds_write_b128 v234, v[52:55]
	ds_write_b128 v234, v[48:51] offset:1280
	ds_write_b128 v234, v[44:47] offset:2560
	ds_write_b128 v234, v[40:43] offset:3840
	ds_write_b128 v234, v[36:39] offset:5120
	ds_write_b128 v234, v[32:35] offset:6400
	ds_write_b128 v234, v[24:27] offset:7680
	ds_write_b128 v234, v[28:31] offset:8960
	ds_read_b128 v[52:55], v235
	ds_read_b128 v[48:51], v235 offset:64
	ds_read_b128 v[44:47], v235 offset:2560
	ds_read_b128 v[40:43], v235 offset:2624
	ds_read_b128 v[36:39], v235 offset:5120
	ds_read_b128 v[32:35], v235 offset:5184
	ds_read_b128 v[24:27], v235 offset:7680
	ds_read_b128 v[28:31], v235 offset:7744
	s_waitcnt lgkmcnt(0)
	v_mfma_f32_16x16x32_bf16 v[84:87], v[80:83], v[16:19], 0
	v_mfma_f32_16x16x32_bf16 v[80:83], v[76:79], v[16:19], 0
	v_mfma_f32_16x16x32_bf16 v[76:79], v[72:75], v[16:19], 0
	v_mfma_f32_16x16x32_bf16 v[72:75], v[120:123], v[16:19], 0
	v_add_u32_e32 v122, 0x51, v116
	v_add_u32_e32 v123, 0x50, v116
	v_cmp_lt_u32_e64 s[8:9], s49, v122
	v_cmp_lt_u32_e32 vcc, s49, v123
	v_add_u32_e32 v120, 0x53, v116
	v_cndmask_b32_e64 v122, 64, 0, s[8:9]
	v_cndmask_b32_e64 v123, v244, 0, vcc
	v_add_u32_e32 v121, 0x52, v116
	v_or3_b32 v95, v95, v122, v123
	v_cmp_lt_u32_e64 s[6:7], s49, v120
	v_cmp_lt_u32_e64 s[10:11], s49, v121
	v_or3_b32 v95, v114, v117, v95
	v_add_u32_e32 v114, 0x43, v116
	v_add_u32_e32 v117, 0x42, v116
	v_cndmask_b32_e64 v120, 16, 0, s[6:7]
	v_cndmask_b32_e64 v121, 32, 0, s[10:11]
	v_cmp_gt_u32_e64 s[16:17], s47, v114
	v_cmp_gt_u32_e64 s[14:15], s47, v117
	v_or3_b32 v95, v120, v121, v95
	v_cndmask_b32_e64 v114, 0, v245, s[16:17]
	v_cndmask_b32_e64 v117, 0, v240, s[14:15]
	v_or3_b32 v95, v114, v95, v117
	v_add_u32_e32 v114, 0x41, v116
	v_mfma_f32_16x16x32_bf16 v[64:67], v[64:67], v[20:23], v[84:87]
	v_cmp_gt_u32_e64 s[24:25], s47, v114
	v_add_u32_e32 v117, 64, v116
	v_add_u32_e32 v120, 51, v116
	v_cndmask_b32_e64 v114, 0, v246, s[24:25]
	v_cmp_gt_u32_e64 s[24:25], s47, v117
	v_mfma_f32_16x16x32_bf16 v[60:63], v[60:63], v[20:23], v[80:83]
	v_add_u32_e32 v121, 50, v116
	v_cndmask_b32_e64 v117, 0, v247, s[24:25]
	v_cmp_gt_u32_e64 s[24:25], s47, v120
	v_or_b32_e32 v114, v114, v117
	v_add_u32_e32 v122, 49, v116
	v_cndmask_b32_e64 v120, 0, v248, s[24:25]
	v_cmp_gt_u32_e64 s[24:25], s47, v121
	v_mfma_f32_16x16x32_bf16 v[56:59], v[56:59], v[20:23], v[76:79]
	v_mul_f32_e32 v64, 0x3e38aa3b, v64
	v_mul_f32_e32 v65, 0x3e38aa3b, v65
	v_cndmask_b32_e64 v121, 0, v249, s[24:25]
	v_cmp_gt_u32_e64 s[24:25], s47, v122
	v_add_u32_e32 v123, 48, v116
	v_mfma_f32_16x16x32_bf16 v[68:71], v[68:71], v[20:23], v[72:75]
	v_cndmask_b32_e64 v64, v241, v64, s[22:23]
	v_cndmask_b32_e64 v65, v65, v241, s[20:21]
	v_mul_f32_e32 v66, 0x3e38aa3b, v66
	v_mul_f32_e32 v67, 0x3e38aa3b, v67
	v_bitop3_b32 v73, v114, s95, v95 bitop3:0xc8
	v_or_b32_e32 v117, v114, v95
	v_or_b32_e32 v120, v120, v121
	v_cndmask_b32_e64 v122, 0, v250, s[24:25]
	v_cmp_gt_u32_e64 s[24:25], s47, v123
	v_max3_f32 v72, v64, s71, v65
	v_cndmask_b32_e64 v66, v66, v241, s[12:13]
	v_cndmask_b32_e64 v67, v67, v241, s[18:19]
	v_mul_f32_e32 v60, 0x3e38aa3b, v60
	v_mul_f32_e32 v61, 0x3e38aa3b, v61
	v_cmp_eq_u32_e64 s[36:37], 0, v73
	v_bitop3_b32 v73, v114, s48, v95 bitop3:0xc8
	v_cndmask_b32_e64 v123, 0, v251, s[24:25]
	v_max3_f32 v72, v72, v66, v67
	v_cndmask_b32_e64 v60, v60, v241, s[6:7]
	v_cndmask_b32_e64 v61, v61, v241, s[10:11]
	v_mul_f32_e32 v62, 0x3e38aa3b, v62
	v_mul_f32_e32 v63, 0x3e38aa3b, v63
	v_cmp_eq_u32_e64 s[26:27], 0, v73
	v_bitop3_b32 v73, v120, s90, v117 bitop3:0xc8
	v_or_b32_e32 v121, v120, v117
	v_or_b32_e32 v122, v122, v123
	v_max3_f32 v72, v72, v60, v61
	v_cndmask_b32_e64 v62, v62, v241, s[8:9]
	v_cndmask_b32_e32 v63, v63, v241, vcc
	v_mul_f32_e32 v56, 0x3e38aa3b, v56
	v_mul_f32_e32 v57, 0x3e38aa3b, v57
	v_cmp_eq_u32_e64 s[34:35], 0, v73
	v_bitop3_b32 v73, v120, s83, v117 bitop3:0xc8
	v_max3_f32 v72, v72, v62, v63
	v_cndmask_b32_e64 v56, v241, v56, s[16:17]
	v_cndmask_b32_e64 v57, v241, v57, s[14:15]
	v_mul_f32_e32 v58, 0x3e38aa3b, v58
	v_mul_f32_e32 v59, 0x3e38aa3b, v59
	v_cmp_eq_u32_e64 s[30:31], 0, v73
	v_bitop3_b32 v73, v122, s50, v121 bitop3:0xc8
	v_max3_f32 v72, v72, v56, v57
	v_cndmask_b32_e64 v58, v58, v241, s[36:37]
	v_cndmask_b32_e64 v59, v59, v241, s[26:27]
	v_mul_f32_e32 v68, 0x3e38aa3b, v68
	v_mul_f32_e32 v69, 0x3e38aa3b, v69
	v_cmp_eq_u32_e64 s[28:29], 0, v73
	v_bitop3_b32 v73, v122, s82, v121 bitop3:0xc8
	v_max3_f32 v72, v72, v58, v59
	v_cndmask_b32_e64 v68, v68, v241, s[34:35]
	v_cndmask_b32_e64 v69, v69, v241, s[30:31]
	v_mul_f32_e32 v70, 0x3e38aa3b, v70
	v_cmp_eq_u32_e64 s[24:25], 0, v73
	v_mul_f32_e32 v71, 0x3e38aa3b, v71
	v_max3_f32 v72, v72, v68, v69
	v_cndmask_b32_e64 v70, v70, v241, s[28:29]
	v_cndmask_b32_e64 v71, v71, v241, s[24:25]
	v_max3_f32 v72, v72, v70, v71
	ds_bpermute_b32 v73, v109, v72
	s_waitcnt lgkmcnt(0)
	v_max_f32_e32 v73, v73, v73
	v_max_f32_e32 v72, v72, v73
	ds_bpermute_b32 v73, v108, v72
	s_waitcnt lgkmcnt(0)
	v_max3_f32 v117, v118, v72, v73
	v_sub_f32_e32 v57, v57, v117
	v_exp_f32_e32 v57, v57
	v_sub_f32_e32 v64, v64, v117
	v_exp_f32_e32 v64, v64
	v_sub_f32_e32 v65, v65, v117
	v_cndmask_b32_e64 v75, 0, v57, s[14:15]
	v_sub_f32_e32 v57, v58, v117
	v_exp_f32_e32 v57, v57
	v_exp_f32_e32 v65, v65
	v_sub_f32_e32 v66, v66, v117
	v_exp_f32_e32 v66, v66
	v_cndmask_b32_e64 v76, v57, 0, s[36:37]
	v_sub_f32_e32 v57, v59, v117
	v_exp_f32_e32 v57, v57
	v_sub_f32_e32 v67, v67, v117
	v_exp_f32_e32 v67, v67
	v_sub_f32_e32 v60, v60, v117
	v_cndmask_b32_e64 v77, v57, 0, s[26:27]
	v_sub_f32_e32 v57, v68, v117
	v_exp_f32_e32 v57, v57
	v_cndmask_b32_e64 v73, 0, v64, s[22:23]
	v_exp_f32_e32 v60, v60
	v_sub_f32_e32 v61, v61, v117
	v_cndmask_b32_e64 v68, v57, 0, s[34:35]
	v_sub_f32_e32 v57, v69, v117
	v_add_f32_e32 v64, 0, v73
	v_cndmask_b32_e64 v65, v65, 0, s[20:21]
	v_exp_f32_e32 v61, v61
	v_sub_f32_e32 v62, v62, v117
	v_exp_f32_e32 v57, v57
	v_add_f32_e32 v64, v65, v64
	v_cndmask_b32_e64 v66, v66, 0, s[12:13]
	v_exp_f32_e32 v62, v62
	v_sub_f32_e32 v63, v63, v117
	v_add_f32_e32 v64, v66, v64
	v_cndmask_b32_e64 v67, v67, 0, s[18:19]
	v_exp_f32_e32 v63, v63
	v_sub_f32_e32 v56, v56, v117
	v_add_f32_e32 v64, v67, v64
	v_cndmask_b32_e64 v60, v60, 0, s[6:7]
	v_exp_f32_e32 v56, v56
	v_add_f32_e32 v64, v60, v64
	v_cndmask_b32_e64 v61, v61, 0, s[10:11]
	v_cndmask_b32_e64 v69, v57, 0, s[30:31]
	v_sub_f32_e32 v57, v70, v117
	v_add_f32_e32 v64, v61, v64
	v_cndmask_b32_e64 v62, v62, 0, s[8:9]
	v_exp_f32_e32 v57, v57
	v_add_f32_e32 v64, v62, v64
	v_cndmask_b32_e64 v63, v63, 0, vcc
	v_add_f32_e32 v64, v63, v64
	v_cndmask_b32_e64 v74, 0, v56, s[16:17]
	v_add_f32_e32 v56, v74, v64
	v_add_f32_e32 v56, v75, v56
	v_cndmask_b32_e64 v70, v57, 0, s[28:29]
	v_sub_f32_e32 v57, v71, v117
	v_sub_f32_e32 v72, v118, v117
	v_add_f32_e32 v56, v76, v56
	v_exp_f32_e32 v57, v57
	v_add_f32_e32 v56, v77, v56
	v_exp_f32_e32 v64, v72
	v_add_f32_e32 v56, v68, v56
	v_add_f32_e32 v56, v69, v56
	v_add_f32_e32 v56, v70, v56
	v_cndmask_b32_e64 v71, v57, 0, s[24:25]
	v_add_f32_e32 v114, v71, v56
	v_cvt_pk_bf16_f32 v56, v73, v65
	v_cvt_pk_bf16_f32 v57, v66, v67
	v_cvt_pk_bf16_f32 v58, v60, v61
	v_cvt_pk_bf16_f32 v59, v62, v63
	v_pk_mul_f32 v[10:11], v[10:11], v[64:65] op_sel_hi:[1,0]
	v_pk_mul_f32 v[8:9], v[8:9], v[64:65] op_sel_hi:[1,0]
	v_pk_mul_f32 v[14:15], v[14:15], v[64:65] op_sel_hi:[1,0]
	v_pk_mul_f32 v[12:13], v[12:13], v[64:65] op_sel_hi:[1,0]
	v_pk_mul_f32 v[6:7], v[6:7], v[64:65] op_sel_hi:[1,0]
	v_pk_mul_f32 v[4:5], v[4:5], v[64:65] op_sel_hi:[1,0]
	v_pk_mul_f32 v[2:3], v[2:3], v[64:65] op_sel_hi:[1,0]
	v_pk_mul_f32 v[0:1], v[0:1], v[64:65] op_sel_hi:[1,0]
	v_mfma_f32_16x16x32_bf16 v[8:11], v[52:55], v[56:59], v[8:11]
	v_cvt_pk_bf16_f32 v60, v74, v75
	v_cvt_pk_bf16_f32 v61, v76, v77
	v_cvt_pk_bf16_f32 v62, v68, v69
	v_mfma_f32_16x16x32_bf16 v[12:15], v[44:47], v[56:59], v[12:15]
	v_cvt_pk_bf16_f32 v63, v70, v71
	v_fmac_f32_e32 v114, v119, v64
	v_mfma_f32_16x16x32_bf16 v[4:7], v[36:39], v[56:59], v[4:7]
	v_mfma_f32_16x16x32_bf16 v[0:3], v[24:27], v[56:59], v[0:3]
	v_mfma_f32_16x16x32_bf16 v[8:11], v[48:51], v[60:63], v[8:11]
	v_mfma_f32_16x16x32_bf16 v[12:15], v[40:43], v[60:63], v[12:15]
	v_mfma_f32_16x16x32_bf16 v[4:7], v[32:35], v[60:63], v[4:7]
	v_mfma_f32_16x16x32_bf16 v[0:3], v[28:31], v[60:63], v[0:3]
	s_cbranch_scc0 .LBB0_619
	s_branch .LBB0_623

.LBB0_623:
	s_ashr_i32 s6, s45, 4
	s_max_i32 s8, s6, 0x80
	s_addk_i32 s8, 0xff80
	s_ashr_i32 s54, s56, 10
	s_lshr_b32 s45, s8, 6
	s_cmp_le_i32 s45, s54
	s_mov_b64 s[6:7], -1
	s_cbranch_scc0 .LBB0_629
	v_mov_b32_e32 v232, 0x4000
	v_add_co_u32_e32 v16, vcc, 0x1800000, v98
	s_and_b32 s7, s44, 15
	s_nop 0
	v_addc_co_u32_e32 v17, vcc, 0, v99, vcc
	global_load_dwordx4 v[32:35], v[16:17], off
	global_load_dwordx4 v[36:39], v[16:17], off offset:64
	v_lshl_or_b32 v16, v210, 4, s7
	v_lshlrev_b32_e32 v136, 7, v16
	v_lshl_add_u64 v[16:17], s[38:39], 0, v[136:137]
	s_mov_b64 s[10:11], 0x1800000
	v_mov_b32_e32 v97, v137
	v_lshl_add_u64 v[48:49], v[16:17], 0, s[10:11]
	v_lshl_add_u64 v[16:17], s[52:53], 0, v[96:97]
	s_lshl_b32 s92, s7, 9
	v_lshl_add_u64 v[16:17], v[16:17], 0, s[92:93]
	s_add_i32 s72, s72, s73
	v_lshl_add_u64 v[16:17], v[16:17], 0, v[208:209]
	s_mov_b32 s41, s93
	s_and_b32 s9, s72, 15
	s_lshr_b32 s92, s8, 6
	v_lshl_add_u64 v[50:51], v[16:17], 0, s[10:11]
	s_and_b32 s6, s8, 0xffffffc0
	s_lshl_b64 s[10:11], s[40:41], 19
	s_lshl_b32 s12, s9, 9
	s_lshl_b64 s[8:9], s[92:93], 7
	s_add_u32 s8, s74, s8
	s_addc_u32 s9, s75, s9
	s_add_u32 s8, s8, s12
	s_addc_u32 s9, s9, 0
	s_add_u32 s8, s8, s10
	v_mov_b32_e32 v95, v137
	s_addc_u32 s9, s9, s11
	v_lshlrev_b32_e32 v116, 2, v112
	v_lshl_add_u64 v[52:53], s[8:9], 0, v[94:95]
	s_lshl_b64 s[8:9], s[92:93], 17
	v_ashrrev_i32_e32 v18, 4, v88
	v_add_u32_e32 v16, s6, v116
	s_add_u32 s8, s10, s8
	v_sub_u32_e32 v64, v16, v18
	v_sub_u32_e32 v16, v18, v116
	s_addc_u32 s9, s11, s9
	s_lshl_b32 s7, s7, 7
	v_subrev_u32_e32 v16, s6, v16
	s_add_u32 s8, s74, s8
	v_add_u32_e32 v65, 0xffffff9d, v16
	v_lshl_or_b32 v136, v210, 11, s7
	s_addc_u32 s9, s75, s9
	s_waitcnt vmcnt(0)
	v_mov_b64_e32 v[30:31], v[10:11]
	v_mov_b64_e32 v[26:27], v[14:15]
	v_mov_b64_e32 v[22:23], v[6:7]
	v_mov_b64_e32 v[18:19], v[2:3]
	v_lshl_add_u64 v[54:55], s[8:9], 0, v[136:137]
	s_mov_b32 s92, s45
	v_mov_b32_e32 v40, v114
	v_mov_b64_e32 v[28:29], v[8:9]
	v_mov_b64_e32 v[24:25], v[12:13]
	v_mov_b64_e32 v[20:21], v[4:5]
	v_mov_b64_e32 v[16:17], v[0:1]
	s_branch .LBB0_626
.LBB0_625:
	v_lshl_add_u64 v[58:59], v[52:53], 0, v[208:209]
	v_add_co_u32_e32 v56, vcc, 0xd060000, v58
	s_mov_b64 s[24:25], vcc
	v_add_co_u32_e32 v60, vcc, 0xd040000, v58
	s_mov_b64 s[6:7], vcc
	v_add_co_u32_e32 v62, vcc, 0xd020000, v58
	s_mov_b64 s[26:27], vcc
	v_add_co_u32_e32 v106, vcc, 0xd000000, v58
	v_lshl_add_u64 v[72:73], v[54:55], 0, v[208:209]
	s_mov_b64 s[28:29], vcc
	v_add_co_u32_e32 v94, vcc, 0xac38000, v72
	v_add_u32_e32 v57, 64, v64
	s_nop 0
	v_addc_co_u32_e32 v95, vcc, 0, v73, vcc
	v_add_co_u32_e32 v84, vcc, 0xac30000, v72
	global_load_dwordx4 v[40:43], v[94:95], off
	s_nop 0
	v_addc_co_u32_e32 v85, vcc, 0, v73, vcc
	v_add_co_u32_e32 v80, vcc, 0xac28000, v72
	global_load_dwordx4 v[44:47], v[84:85], off
	s_nop 0
	v_addc_co_u32_e32 v81, vcc, 0, v73, vcc
	global_load_dwordx4 v[68:71], v[80:81], off
	v_add_co_u32_e32 v76, vcc, 0xac20000, v72
	v_add_u32_e32 v100, 0xffffff90, v65
	s_nop 0
	v_addc_co_u32_e32 v77, vcc, 0, v73, vcc
	global_load_dwordx4 v[72:75], v[76:77], off
	s_nop 0
	v_lshl_add_u64 v[236:237], v[76:77], 0, v[232:233]
	global_load_dwordx4 v[76:79], v[236:237], off
	s_nop 0
	v_lshl_add_u64 v[236:237], v[80:81], 0, v[232:233]
	global_load_dwordx4 v[80:83], v[236:237], off
	s_nop 0
	v_lshl_add_u64 v[236:237], v[84:85], 0, v[232:233]
	global_load_dwordx4 v[84:87], v[236:237], off
	s_nop 0
	v_lshl_add_u64 v[236:237], v[94:95], 0, v[232:233]
	global_load_dwordx4 v[94:97], v[236:237], off
	v_add_u32_e32 v101, 0xffffff8f, v65
	v_add_u32_e32 v61, 0xffffffa0, v65
	v_add_u32_e32 v63, 0xffffff9f, v65
	v_add_u32_e32 v98, 0xffffff92, v65
	v_add_u32_e32 v99, 0xffffff91, v65
	v_cmp_gt_u32_e64 s[20:21], s88, v57
	v_cmp_gt_u32_e64 s[12:13], s88, v100
	v_cmp_gt_u32_e64 s[14:15], s88, v101
	v_add_u32_e32 v104, 1, v65
	v_cndmask_b32_e64 v107, 2, 0, s[20:21]
	v_cmp_gt_u32_e64 s[22:23], s88, v61
	v_cmp_gt_u32_e64 s[16:17], s88, v63
	v_cmp_gt_u32_e64 s[18:19], s88, v98
	v_cmp_gt_u32_e64 s[10:11], s88, v99
	v_cndmask_b32_e64 v98, 64, 0, s[12:13]
	v_cndmask_b32_e64 v99, v244, 0, s[14:15]
	v_add_u32_e32 v102, 3, v65
	v_add_u32_e32 v103, 2, v65
	v_cmp_gt_u32_e32 vcc, s47, v65
	v_cndmask_b32_e64 v61, 4, 0, s[22:23]
	v_cndmask_b32_e64 v63, 8, 0, s[16:17]
	v_cmp_gt_u32_e64 s[30:31], s47, v104
	v_or3_b32 v98, v98, v99, v107
	v_cndmask_b32_e32 v105, 0, v247, vcc
	v_add_u32_e32 v111, -13, v65
	v_cndmask_b32_e64 v112, 16, 0, s[18:19]
	v_cndmask_b32_e64 v113, 32, 0, s[10:11]
	v_cmp_gt_u32_e32 vcc, s47, v102
	v_cmp_gt_u32_e64 s[8:9], s47, v103
	v_cndmask_b32_e64 v100, 0, v246, s[30:31]
	v_addc_co_u32_e64 v57, s[24:25], 0, v59, s[24:25]
	v_or3_b32 v61, v61, v63, v98
	v_addc_co_u32_e64 v63, s[24:25], 0, v59, s[26:27]
	v_addc_co_u32_e64 v107, s[24:25], 0, v59, s[28:29]
	v_cndmask_b32_e32 v117, 0, v245, vcc
	v_cndmask_b32_e64 v118, 0, v240, s[8:9]
	v_or_b32_e32 v119, v100, v105
	v_cmp_gt_u32_e64 s[24:25], s47, v111
	v_add_u32_e32 v111, -14, v65
	v_add_u32_e32 v58, 35, v65
	v_cmp_gt_u32_e64 s[36:37], s47, v58
	s_add_i32 s45, s45, 2
	s_min_i32 s92, s45, s54
	v_add_u32_e32 v64, 0x80, v64
	v_lshl_add_u64 v[54:55], v[54:55], 0, s[78:79]
	s_waitcnt vmcnt(0) lgkmcnt(0)
	ds_write_b128 v234, v[40:43]
	ds_write_b128 v234, v[94:97] offset:1280
	ds_write_b128 v234, v[44:47] offset:2560
	ds_write_b128 v234, v[84:87] offset:3840
	ds_write_b128 v234, v[68:71] offset:5120
	ds_write_b128 v234, v[80:83] offset:6400
	ds_write_b128 v234, v[72:75] offset:7680
	ds_write_b128 v234, v[76:79] offset:8960
	ds_read_b128 v[40:43], v235
	ds_read_b128 v[94:97], v235 offset:64
	ds_read_b128 v[44:47], v235 offset:2560
	ds_read_b128 v[84:87], v235 offset:2624
	ds_read_b128 v[68:71], v235 offset:5120
	ds_read_b128 v[80:83], v235 offset:5184
	ds_read_b128 v[72:75], v235 offset:7680
	ds_read_b128 v[76:79], v235 offset:7744
	s_waitcnt lgkmcnt(0)
	v_mfma_f32_16x16x32_bf16 v[72:75], v[72:75], v[32:35], 0
	v_mfma_f32_16x16x32_bf16 v[68:71], v[68:71], v[32:35], 0
	v_mfma_f32_16x16x32_bf16 v[98:101], v[40:43], v[32:35], 0
	v_or3_b32 v40, v112, v113, v61
	v_or3_b32 v61, v117, v40, v118
	v_mfma_f32_16x16x32_bf16 v[102:105], v[44:47], v[32:35], 0
	v_lshl_add_u64 v[236:237], v[106:107], 0, v[214:215]
	global_load_dwordx4 v[40:43], v[236:237], off offset:128
	global_load_dwordx4 v[44:47], v[106:107], off offset:128
	v_cndmask_b32_e64 v107, 0, v248, s[24:25]
	v_cmp_gt_u32_e64 s[24:25], s47, v111
	v_mfma_f32_16x16x32_bf16 v[68:71], v[80:83], v[36:39], v[68:71]
	v_add_u32_e32 v81, -16, v65
	v_cndmask_b32_e64 v111, 0, v249, s[24:25]
	v_or_b32_e32 v106, v119, v61
	v_mfma_f32_16x16x32_bf16 v[72:75], v[76:79], v[36:39], v[72:75]
	v_add_u32_e32 v76, -15, v65
	v_cmp_gt_u32_e64 s[24:25], s47, v76
	s_nop 1
	v_mul_f32_e32 v68, 0x3e38aa3b, v68
	v_mfma_f32_16x16x32_bf16 v[76:79], v[84:87], v[36:39], v[102:105]
	v_cndmask_b32_e64 v80, 0, v250, s[24:25]
	v_cmp_gt_u32_e64 s[24:25], s47, v81
	v_mul_f32_e32 v72, 0x3e38aa3b, v72
	v_mul_f32_e32 v58, 0x3e38aa3b, v73
	v_cndmask_b32_e64 v81, 0, v251, s[24:25]
	v_or_b32_e32 v84, v80, v81
	v_mfma_f32_16x16x32_bf16 v[80:83], v[94:97], v[36:39], v[98:101]
	v_cndmask_b32_e64 v94, v241, v72, s[36:37]
	v_mul_f32_e32 v72, 0x3e38aa3b, v74
	v_cndmask_b32_e64 v95, v58, v241, s[20:21]
	v_cndmask_b32_e64 v98, v68, v241, s[18:19]
	v_mul_f32_e32 v68, 0x3e38aa3b, v69
	v_cndmask_b32_e64 v99, v68, v241, s[10:11]
	v_mul_f32_e32 v68, 0x3e38aa3b, v70
	v_cndmask_b32_e64 v100, v68, v241, s[12:13]
	v_mul_f32_e32 v68, 0x3e38aa3b, v71
	v_cndmask_b32_e64 v101, v68, v241, s[14:15]
	v_mul_f32_e32 v68, 0x3e38aa3b, v76
	v_cndmask_b32_e64 v96, v72, v241, s[22:23]
	v_mul_f32_e32 v72, 0x3e38aa3b, v75
	v_cndmask_b32_e32 v102, v241, v68, vcc
	v_mul_f32_e32 v68, 0x3e38aa3b, v77
	v_or_b32_e32 v107, v107, v111
	v_max3_f32 v58, v94, s71, v95
	v_cndmask_b32_e64 v97, v72, v241, s[16:17]
	v_cndmask_b32_e64 v103, v241, v68, s[8:9]
	v_bitop3_b32 v68, v119, s95, v61 bitop3:0xc8
	v_bitop3_b32 v61, v119, s48, v61 bitop3:0xc8
	v_max3_f32 v58, v58, v96, v97
	v_cmp_eq_u32_e64 s[28:29], 0, v68
	v_mul_f32_e32 v68, 0x3e38aa3b, v79
	v_cmp_eq_u32_e64 s[34:35], 0, v61
	v_bitop3_b32 v61, v107, s90, v106 bitop3:0xc8
	v_or_b32_e32 v111, v107, v106
	v_max3_f32 v58, v58, v98, v99
	v_cndmask_b32_e64 v105, v68, v241, s[34:35]
	v_mul_f32_e32 v68, 0x3e38aa3b, v80
	v_cmp_eq_u32_e64 s[24:25], 0, v61
	v_bitop3_b32 v61, v107, s83, v106 bitop3:0xc8
	v_max3_f32 v58, v58, v100, v101
	v_mul_f32_e32 v69, 0x3e38aa3b, v78
	v_cndmask_b32_e64 v112, v68, v241, s[24:25]
	v_mul_f32_e32 v68, 0x3e38aa3b, v81
	v_cmp_eq_u32_e64 s[26:27], 0, v61
	v_bitop3_b32 v61, v84, s50, v111 bitop3:0xc8
	v_max3_f32 v58, v58, v102, v103
	v_cndmask_b32_e64 v104, v69, v241, s[28:29]
	v_cndmask_b32_e64 v106, v68, v241, s[26:27]
	v_mul_f32_e32 v68, 0x3e38aa3b, v82
	v_cmp_eq_u32_e64 s[30:31], 0, v61
	v_bitop3_b32 v61, v84, s82, v111 bitop3:0xc8
	v_max3_f32 v58, v58, v104, v105
	v_cndmask_b32_e64 v107, v68, v241, s[30:31]
	v_mul_f32_e32 v68, 0x3e38aa3b, v83
	v_cmp_eq_u32_e64 s[38:39], 0, v61
	v_max3_f32 v58, v58, v112, v106
	v_addc_co_u32_e64 v61, s[6:7], 0, v59, s[6:7]
	v_cndmask_b32_e64 v111, v68, v241, s[38:39]
	v_max3_f32 v58, v58, v107, v111
	ds_bpermute_b32 v76, v109, v58
	v_lshl_add_u64 v[236:237], v[62:63], 0, v[214:215]
	global_load_dwordx4 v[68:71], v[236:237], off offset:128
	global_load_dwordx4 v[72:75], v[62:63], off offset:128
	s_lshl_b32 s6, s92, 6
	s_cmp_gt_i32 s45, s54
	v_add_u32_e32 v65, 0xffffff80, v65
	s_waitcnt lgkmcnt(0)
	v_max_f32_e32 v59, v76, v76
	v_max_f32_e32 v62, v58, v59
	v_lshl_add_u64 v[236:237], v[60:61], 0, v[214:215]
	global_load_dwordx4 v[76:79], v[236:237], off offset:128
	s_nop 0
	global_load_dwordx4 v[58:61], v[60:61], off offset:128
	s_nop 0
	v_lshl_add_u64 v[236:237], v[56:57], 0, v[214:215]
	global_load_dwordx4 v[80:83], v[236:237], off offset:128
	global_load_dwordx4 v[84:87], v[56:57], off offset:128
	ds_bpermute_b32 v63, v108, v62
	s_waitcnt lgkmcnt(0)
	v_max3_f32 v117, v67, v62, v63
	v_sub_f32_e32 v56, v94, v117
	v_exp_f32_e32 v56, v56
	v_sub_f32_e32 v57, v67, v117
	v_sub_f32_e32 v63, v96, v117
	v_exp_f32_e32 v63, v63
	v_cndmask_b32_e64 v62, 0, v56, s[36:37]
	v_sub_f32_e32 v56, v95, v117
	v_exp_f32_e32 v56, v56
	v_add_f32_e32 v67, 0, v62
	v_sub_f32_e32 v95, v98, v117
	v_exp_f32_e32 v95, v95
	v_cndmask_b32_e64 v94, v56, 0, s[20:21]
	v_add_f32_e32 v56, v94, v67
	v_sub_f32_e32 v67, v97, v117
	v_exp_f32_e32 v67, v67
	v_cndmask_b32_e64 v63, v63, 0, s[22:23]
	v_add_f32_e32 v56, v63, v56
	v_cndmask_b32_e64 v96, v95, 0, s[18:19]
	v_cndmask_b32_e64 v67, v67, 0, s[16:17]
	v_add_f32_e32 v56, v67, v56
	v_sub_f32_e32 v95, v99, v117
	v_sub_f32_e32 v97, v100, v117
	v_exp_f32_e32 v95, v95
	v_exp_f32_e32 v97, v97
	v_add_f32_e32 v113, v96, v56
	v_sub_f32_e32 v56, v102, v117
	v_exp_f32_e32 v56, v56
	v_sub_f32_e32 v98, v101, v117
	v_exp_f32_e32 v98, v98
	v_cndmask_b32_e64 v118, v95, 0, s[10:11]
	v_cndmask_b32_e64 v119, v97, 0, s[12:13]
	v_sub_f32_e32 v95, v103, v117
	v_sub_f32_e32 v97, v104, v117
	v_exp_f32_e32 v95, v95
	v_exp_f32_e32 v97, v97
	v_cndmask_b32_e32 v102, 0, v56, vcc
	v_sub_f32_e32 v56, v112, v117
	v_exp_f32_e32 v56, v56
	v_cndmask_b32_e64 v120, v98, 0, s[14:15]
	v_sub_f32_e32 v98, v105, v117
	v_exp_f32_e32 v98, v98
	v_cndmask_b32_e64 v103, 0, v95, s[8:9]
	v_cndmask_b32_e64 v104, v97, 0, s[28:29]
	v_sub_f32_e32 v95, v106, v117
	v_sub_f32_e32 v97, v107, v117
	v_exp_f32_e32 v95, v95
	v_exp_f32_e32 v97, v97
	v_cndmask_b32_e64 v106, v56, 0, s[24:25]
	v_exp_f32_e32 v56, v57
	v_cndmask_b32_e64 v105, v98, 0, s[34:35]
	v_sub_f32_e32 v98, v111, v117
	v_exp_f32_e32 v98, v98
	v_cndmask_b32_e64 v107, v95, 0, s[26:27]
	v_cndmask_b32_e64 v111, v97, 0, s[30:31]
	v_cvt_pk_bf16_f32 v94, v62, v94
	v_cvt_pk_bf16_f32 v95, v63, v67
	v_cvt_pk_bf16_f32 v96, v96, v118
	v_cvt_pk_bf16_f32 v97, v119, v120
	v_pk_mul_f32 v[30:31], v[30:31], v[56:57] op_sel_hi:[1,0]
	v_pk_mul_f32 v[28:29], v[28:29], v[56:57] op_sel_hi:[1,0]
	v_cndmask_b32_e64 v112, v98, 0, s[38:39]
	v_cvt_pk_bf16_f32 v98, v102, v103
	s_waitcnt vmcnt(0)
	ds_write_b128 v234, v[44:47]
	ds_write_b128 v234, v[40:43] offset:1280
	ds_write_b128 v234, v[72:75] offset:2560
	ds_write_b128 v234, v[68:71] offset:3840
	ds_write_b128 v234, v[58:61] offset:5120
	ds_write_b128 v234, v[76:79] offset:6400
	ds_write_b128 v234, v[84:87] offset:7680
	ds_write_b128 v234, v[80:83] offset:8960
	ds_read_b128 v[44:47], v235
	ds_read_b128 v[40:43], v235 offset:64
	ds_read_b128 v[72:75], v235 offset:2560
	ds_read_b128 v[68:71], v235 offset:2624
	ds_read_b128 v[58:61], v235 offset:5120
	ds_read_b128 v[76:79], v235 offset:5184
	ds_read_b128 v[84:87], v235 offset:7680
	ds_read_b128 v[80:83], v235 offset:7744
	s_waitcnt lgkmcnt(0)
	v_mfma_f32_16x16x32_bf16 v[28:31], v[44:47], v[94:97], v[28:31]
	v_cvt_pk_bf16_f32 v99, v104, v105
	v_cvt_pk_bf16_f32 v100, v106, v107
	v_cvt_pk_bf16_f32 v101, v111, v112
	v_pk_mul_f32 v[26:27], v[26:27], v[56:57] op_sel_hi:[1,0]
	v_pk_mul_f32 v[24:25], v[24:25], v[56:57] op_sel_hi:[1,0]
	v_mfma_f32_16x16x32_bf16 v[28:31], v[40:43], v[98:101], v[28:31]
	v_add_f32_e32 v40, v118, v113
	v_add_f32_e32 v40, v119, v40
	v_add_f32_e32 v40, v120, v40
	v_add_f32_e32 v40, v102, v40
	v_add_f32_e32 v40, v103, v40
	v_pk_mul_f32 v[22:23], v[22:23], v[56:57] op_sel_hi:[1,0]
	v_pk_mul_f32 v[20:21], v[20:21], v[56:57] op_sel_hi:[1,0]
	v_pk_mul_f32 v[18:19], v[18:19], v[56:57] op_sel_hi:[1,0]
	v_pk_mul_f32 v[16:17], v[16:17], v[56:57] op_sel_hi:[1,0]
	v_mfma_f32_16x16x32_bf16 v[24:27], v[72:75], v[94:97], v[24:27]
	v_add_f32_e32 v40, v104, v40
	v_add_f32_e32 v40, v105, v40
	v_add_f32_e32 v40, v106, v40
	v_mfma_f32_16x16x32_bf16 v[20:23], v[58:61], v[94:97], v[20:23]
	v_add_f32_e32 v40, v107, v40
	v_add_f32_e32 v40, v111, v40
	v_add_f32_e32 v40, v112, v40
	v_mfma_f32_16x16x32_bf16 v[16:19], v[84:87], v[94:97], v[16:19]
	v_fmac_f32_e32 v40, v66, v56
	s_mov_b64 s[8:9], 0x100
	v_lshl_add_u64 v[52:53], v[52:53], 0, s[8:9]
	v_mfma_f32_16x16x32_bf16 v[24:27], v[68:71], v[98:101], v[24:27]
	s_cselect_b64 s[8:9], -1, 0
	v_mov_b32_e32 v66, v40
	v_mfma_f32_16x16x32_bf16 v[20:23], v[76:79], v[98:101], v[20:23]
	v_mfma_f32_16x16x32_bf16 v[16:19], v[80:83], v[98:101], v[16:19]
	s_andn2_b64 vcc, exec, s[8:9]
	s_cbranch_vccz .LBB0_628
.LBB0_626:
	s_lshl_b64 s[8:9], s[92:93], 17
	v_lshl_add_u64 v[42:43], v[48:49], 0, s[8:9]
	v_lshl_add_u64 v[46:47], v[212:213], 1, v[42:43]
	global_load_dwordx4 v[42:45], v[46:47], off
	v_add_co_u32_e32 v74, vcc, s82, v46
	v_add_u32_e32 v100, 0x41, v65
	s_nop 0
	v_addc_co_u32_e32 v75, vcc, 0, v47, vcc
	global_load_dwordx4 v[56:59], v[74:75], off
	v_add_co_u32_e32 v78, vcc, s94, v46
	v_add_u32_e32 v101, 64, v65
	s_nop 0
	v_addc_co_u32_e32 v79, vcc, 0, v47, vcc
	global_load_dwordx4 v[60:63], v[78:79], off
	v_add_co_u32_e32 v82, vcc, s51, v46
	v_cmp_gt_u32_e64 s[22:23], s47, v100
	s_nop 0
	v_addc_co_u32_e32 v83, vcc, 0, v47, vcc
	global_load_dwordx4 v[66:69], v[82:83], off
	v_lshl_add_u64 v[236:237], v[46:47], 0, v[232:233]
	global_load_dwordx4 v[70:73], v[236:237], off
	s_nop 0
	v_lshl_add_u64 v[236:237], v[74:75], 0, v[232:233]
	global_load_dwordx4 v[74:77], v[236:237], off
	s_nop 0
	v_lshl_add_u64 v[236:237], v[78:79], 0, v[232:233]
	global_load_dwordx4 v[78:81], v[236:237], off
	s_nop 0
	v_lshl_add_u64 v[236:237], v[82:83], 0, v[232:233]
	global_load_dwordx4 v[82:85], v[236:237], off
	v_add_u32_e32 v103, 51, v65
	v_cndmask_b32_e64 v122, 0, v246, s[22:23]
	v_cmp_gt_u32_e64 s[22:23], s47, v101
	v_add_u32_e32 v104, 50, v65
	v_add_u32_e32 v105, 49, v65
	v_cndmask_b32_e64 v123, 0, v247, s[22:23]
	v_cmp_gt_u32_e64 s[22:23], s47, v103
	s_mov_b32 s7, s93
	v_add_u32_e32 v41, 0x63, v65
	v_cndmask_b32_e64 v103, 0, v248, s[22:23]
	v_cmp_gt_u32_e64 s[22:23], s47, v104
	v_add_u32_e32 v96, 0x51, v65
	v_add_u32_e32 v97, 0x50, v65
	v_add_u32_e32 v106, 48, v65
	v_cndmask_b32_e64 v104, 0, v249, s[22:23]
	v_cmp_gt_u32_e64 s[22:23], s47, v105
	v_cmp_gt_u32_e32 vcc, s88, v64
	v_add_u32_e32 v86, 0x61, v65
	v_add_u32_e32 v87, 0x60, v65
	v_lshl_add_u64 v[46:47], s[6:7], 1, v[50:51]
	v_cmp_lt_u32_e64 s[12:13], s49, v96
	v_cmp_lt_u32_e64 s[14:15], s49, v97
	v_cndmask_b32_e64 v105, 0, v250, s[22:23]
	v_cmp_gt_u32_e64 s[22:23], s47, v106
	v_cmp_gt_u32_e64 s[30:31], s47, v41
	v_cndmask_b32_e64 v102, 2, 0, vcc
	v_add_u32_e32 v94, 0x53, v65
	v_add_u32_e32 v95, 0x52, v65
	v_cmp_lt_u32_e64 s[20:21], s49, v86
	v_cmp_lt_u32_e64 s[16:17], s49, v87
	v_cndmask_b32_e64 v118, 64, 0, s[12:13]
	v_cndmask_b32_e64 v119, v244, 0, s[14:15]
	v_cndmask_b32_e64 v106, 0, v251, s[22:23]
	v_add_co_u32_e64 v86, s[22:23], s0, v46
	v_add_u32_e32 v98, 0x43, v65
	v_add_u32_e32 v99, 0x42, v65
	v_cndmask_b32_e64 v107, 4, 0, s[20:21]
	v_cndmask_b32_e64 v111, 8, 0, s[16:17]
	v_cmp_lt_u32_e64 s[18:19], s49, v94
	v_cmp_lt_u32_e64 s[10:11], s49, v95
	v_addc_co_u32_e64 v87, s[22:23], 0, v47, s[22:23]
	v_or3_b32 v102, v102, v118, v119
	v_cndmask_b32_e64 v112, 16, 0, s[18:19]
	v_cndmask_b32_e64 v113, 32, 0, s[10:11]
	v_cmp_gt_u32_e64 s[6:7], s47, v98
	v_cmp_gt_u32_e64 s[8:9], s47, v99
	global_load_dwordx4 v[94:97], v[46:47], off
	v_lshl_add_u64 v[236:237], v[46:47], 0, v[214:215]
	global_load_dwordx4 v[98:101], v[236:237], off
	v_cndmask_b32_e64 v120, 0, v245, s[6:7]
	v_cndmask_b32_e64 v121, 0, v240, s[8:9]
	v_or_b32_e32 v118, v122, v123
	v_or_b32_e32 v103, v103, v104
	v_or_b32_e32 v104, v105, v106
	s_mov_b32 s38, 0x40000
	s_cmp_ge_i32 s45, s54
	s_waitcnt vmcnt(0) lgkmcnt(0)
	ds_write_b128 v234, v[42:45]
	ds_write_b128 v234, v[70:73] offset:1280
	ds_write_b128 v234, v[56:59] offset:2560
	ds_write_b128 v234, v[74:77] offset:3840
	ds_write_b128 v234, v[60:63] offset:5120
	ds_write_b128 v234, v[78:81] offset:6400
	ds_write_b128 v234, v[66:69] offset:7680
	ds_write_b128 v234, v[82:85] offset:8960
	ds_read_b128 v[42:45], v235
	ds_read_b128 v[70:73], v235 offset:64
	ds_read_b128 v[56:59], v235 offset:2560
	ds_read_b128 v[74:77], v235 offset:2624
	ds_read_b128 v[60:63], v235 offset:5120
	ds_read_b128 v[78:81], v235 offset:5184
	ds_read_b128 v[66:69], v235 offset:7680
	ds_read_b128 v[82:85], v235 offset:7744
	ds_write_b128 v234, v[94:97]
	ds_write_b128 v234, v[98:101] offset:1280
	ds_read_b128 v[94:97], v235
	ds_read_b128 v[98:101], v235 offset:64
	s_waitcnt lgkmcnt(0)
	v_mfma_f32_16x16x32_bf16 v[66:69], v[66:69], v[32:35], 0
	v_mfma_f32_16x16x32_bf16 v[42:45], v[42:45], v[32:35], 0
	v_mfma_f32_16x16x32_bf16 v[56:59], v[56:59], v[32:35], 0
	v_mfma_f32_16x16x32_bf16 v[42:45], v[70:73], v[36:39], v[42:45]
	v_mfma_f32_16x16x32_bf16 v[60:63], v[60:63], v[32:35], 0
	v_mfma_f32_16x16x32_bf16 v[56:59], v[74:77], v[36:39], v[56:59]
	s_nop 5
	v_mul_f32_e32 v42, 0x3e38aa3b, v42
	v_cndmask_b32_e64 v41, v241, v42, s[30:31]
	v_mul_f32_e32 v42, 0x3e38aa3b, v43
	v_mul_f32_e32 v43, 0x3e38aa3b, v44
	v_mfma_f32_16x16x32_bf16 v[66:69], v[82:85], v[36:39], v[66:69]
	v_cndmask_b32_e64 v83, v43, v241, s[20:21]
	v_mul_f32_e32 v43, 0x3e38aa3b, v45
	global_load_dwordx4 v[70:73], v[86:87], off
	v_lshl_add_u64 v[236:237], v[86:87], 0, v[214:215]
	global_load_dwordx4 v[74:77], v[236:237], off
	v_or3_b32 v86, v107, v111, v102
	v_mfma_f32_16x16x32_bf16 v[60:63], v[78:81], v[36:39], v[60:63]
	v_cndmask_b32_e64 v84, v43, v241, s[16:17]
	v_mul_f32_e32 v43, 0x3e38aa3b, v56
	v_or3_b32 v86, v112, v113, v86
	v_cndmask_b32_e64 v85, v43, v241, s[18:19]
	v_mul_f32_e32 v43, 0x3e38aa3b, v57
	v_or3_b32 v78, v120, v86, v121
	v_cndmask_b32_e64 v86, v43, v241, s[10:11]
	v_mul_f32_e32 v43, 0x3e38aa3b, v58
	v_cndmask_b32_e64 v87, v43, v241, s[12:13]
	v_mul_f32_e32 v43, 0x3e38aa3b, v59
	v_cndmask_b32_e64 v102, v43, v241, s[14:15]
	v_mul_f32_e32 v43, 0x3e38aa3b, v60
	v_cndmask_b32_e64 v105, v241, v43, s[6:7]
	v_mul_f32_e32 v43, 0x3e38aa3b, v61
	v_cndmask_b32_e32 v82, v42, v241, vcc
	v_cndmask_b32_e64 v106, v241, v43, s[8:9]
	v_bitop3_b32 v43, v118, s95, v78 bitop3:0xc8
	v_or_b32_e32 v79, v118, v78
	v_max3_f32 v42, v41, s71, v82
	v_mul_f32_e32 v44, 0x3e38aa3b, v62
	v_cmp_eq_u32_e64 s[26:27], 0, v43
	v_bitop3_b32 v43, v118, s48, v78 bitop3:0xc8
	v_max3_f32 v42, v42, v83, v84
	v_cndmask_b32_e64 v107, v44, v241, s[26:27]
	v_mul_f32_e32 v44, 0x3e38aa3b, v63
	v_cmp_eq_u32_e64 s[34:35], 0, v43
	v_bitop3_b32 v43, v103, s90, v79 bitop3:0xc8
	v_or_b32_e32 v80, v103, v79
	v_max3_f32 v42, v42, v85, v86
	v_cndmask_b32_e64 v111, v44, v241, s[34:35]
	v_mul_f32_e32 v44, 0x3e38aa3b, v66
	v_cmp_eq_u32_e64 s[22:23], 0, v43
	v_bitop3_b32 v43, v103, s83, v79 bitop3:0xc8
	v_max3_f32 v42, v42, v87, v102
	v_cndmask_b32_e64 v66, v44, v241, s[22:23]
	v_mul_f32_e32 v44, 0x3e38aa3b, v67
	v_cmp_eq_u32_e64 s[24:25], 0, v43
	v_bitop3_b32 v43, v104, s50, v80 bitop3:0xc8
	v_max3_f32 v42, v42, v105, v106
	v_cndmask_b32_e64 v103, v44, v241, s[24:25]
	v_mul_f32_e32 v44, 0x3e38aa3b, v68
	v_cmp_eq_u32_e64 s[28:29], 0, v43
	v_bitop3_b32 v43, v104, s82, v80 bitop3:0xc8
	v_max3_f32 v42, v42, v107, v111
	v_cndmask_b32_e64 v68, v44, v241, s[28:29]
	v_mul_f32_e32 v44, 0x3e38aa3b, v69
	v_cmp_eq_u32_e64 s[36:37], 0, v43
	v_max3_f32 v42, v42, v66, v103
	v_add_co_u32_e64 v56, s[38:39], s38, v46
	v_cndmask_b32_e64 v69, v44, v241, s[36:37]
	v_max3_f32 v60, v42, v68, v69
	ds_bpermute_b32 v61, v109, v60
	v_addc_co_u32_e64 v57, s[38:39], 0, v47, s[38:39]
	v_add_co_u32_e64 v46, s[38:39], s76, v46
	s_waitcnt lgkmcnt(0)
	v_max_f32_e32 v61, v61, v61
	v_max_f32_e32 v60, v60, v61
	ds_bpermute_b32 v61, v108, v60
	v_addc_co_u32_e64 v47, s[38:39], 0, v47, s[38:39]
	global_load_dwordx4 v[42:45], v[56:57], off
	s_nop 0
	v_lshl_add_u64 v[236:237], v[56:57], 0, v[214:215]
	global_load_dwordx4 v[56:59], v[236:237], off
	s_waitcnt lgkmcnt(0)
	v_max3_f32 v67, v117, v60, v61
	global_load_dwordx4 v[60:63], v[46:47], off
	v_lshl_add_u64 v[236:237], v[46:47], 0, v[214:215]
	global_load_dwordx4 v[78:81], v[236:237], off
	v_sub_f32_e32 v47, v82, v67
	v_sub_f32_e32 v82, v83, v67
	v_exp_f32_e32 v82, v82
	v_sub_f32_e32 v41, v41, v67
	v_exp_f32_e32 v41, v41
	v_exp_f32_e32 v47, v47
	v_cndmask_b32_e64 v104, v82, 0, s[20:21]
	v_sub_f32_e32 v82, v84, v67
	v_exp_f32_e32 v82, v82
	v_cndmask_b32_e64 v41, 0, v41, s[30:31]
	v_add_f32_e32 v83, 0, v41
	v_cndmask_b32_e64 v47, v47, 0, vcc
	v_add_f32_e32 v83, v47, v83
	v_sub_f32_e32 v84, v85, v67
	v_add_f32_e32 v83, v104, v83
	v_cndmask_b32_e64 v85, v82, 0, s[16:17]
	v_exp_f32_e32 v84, v84
	v_add_f32_e32 v82, v85, v83
	v_sub_f32_e32 v83, v86, v67
	v_exp_f32_e32 v83, v83
	v_cndmask_b32_e64 v84, v84, 0, s[18:19]
	v_add_f32_e32 v82, v84, v82
	v_sub_f32_e32 v86, v87, v67
	v_sub_f32_e32 v87, v102, v67
	v_cndmask_b32_e64 v102, v83, 0, s[10:11]
	v_add_f32_e32 v112, v102, v82
	v_sub_f32_e32 v82, v105, v67
	v_exp_f32_e32 v82, v82
	v_exp_f32_e32 v86, v86
	v_sub_f32_e32 v105, v107, v67
	v_exp_f32_e32 v87, v87
	v_cndmask_b32_e64 v107, 0, v82, s[6:7]
	v_sub_f32_e32 v82, v103, v67
	v_exp_f32_e32 v82, v82
	v_sub_f32_e32 v46, v117, v67
	v_sub_f32_e32 v83, v106, v67
	v_exp_f32_e32 v83, v83
	v_exp_f32_e32 v46, v46
	v_cndmask_b32_e64 v86, v86, 0, s[12:13]
	v_exp_f32_e32 v105, v105
	v_sub_f32_e32 v106, v111, v67
	v_cndmask_b32_e64 v87, v87, 0, s[14:15]
	v_exp_f32_e32 v106, v106
	v_sub_f32_e32 v66, v66, v67
	v_sub_f32_e32 v68, v68, v67
	v_sub_f32_e32 v69, v69, v67
	v_cndmask_b32_e64 v117, v82, 0, s[24:25]
	v_cvt_pk_bf16_f32 v82, v41, v47
	v_add_f32_e32 v41, v86, v112
	v_exp_f32_e32 v66, v66
	v_exp_f32_e32 v68, v68
	v_exp_f32_e32 v69, v69
	v_add_f32_e32 v41, v87, v41
	v_cndmask_b32_e64 v111, 0, v83, s[8:9]
	v_cvt_pk_bf16_f32 v83, v104, v85
	v_cvt_pk_bf16_f32 v84, v84, v102
	v_cvt_pk_bf16_f32 v85, v86, v87
	v_pk_mul_f32 v[30:31], v[30:31], v[46:47] op_sel_hi:[1,0]
	v_pk_mul_f32 v[28:29], v[28:29], v[46:47] op_sel_hi:[1,0]
	v_pk_mul_f32 v[26:27], v[26:27], v[46:47] op_sel_hi:[1,0]
	v_pk_mul_f32 v[24:25], v[24:25], v[46:47] op_sel_hi:[1,0]
	v_add_f32_e32 v41, v107, v41
	v_pk_mul_f32 v[22:23], v[22:23], v[46:47] op_sel_hi:[1,0]
	v_pk_mul_f32 v[20:21], v[20:21], v[46:47] op_sel_hi:[1,0]
	v_pk_mul_f32 v[18:19], v[18:19], v[46:47] op_sel_hi:[1,0]
	v_pk_mul_f32 v[16:17], v[16:17], v[46:47] op_sel_hi:[1,0]
	v_cndmask_b32_e64 v113, v105, 0, s[26:27]
	v_mfma_f32_16x16x32_bf16 v[28:31], v[94:97], v[82:85], v[28:31]
	v_add_f32_e32 v41, v111, v41
	v_cndmask_b32_e64 v106, v106, 0, s[34:35]
	v_add_f32_e32 v41, v113, v41
	s_waitcnt vmcnt(0)
	ds_write_b128 v234, v[70:73]
	ds_write_b128 v234, v[74:77] offset:1280
	ds_write_b128 v234, v[42:45] offset:2560
	ds_write_b128 v234, v[56:59] offset:3840
	ds_write_b128 v234, v[60:63] offset:5120
	ds_write_b128 v234, v[78:81] offset:6400
	ds_read_b128 v[70:73], v235
	ds_read_b128 v[74:77], v235 offset:64
	ds_read_b128 v[42:45], v235 offset:2560
	ds_read_b128 v[56:59], v235 offset:2624
	ds_read_b128 v[60:63], v235 offset:5120
	ds_read_b128 v[78:81], v235 offset:5184
	s_waitcnt lgkmcnt(0)
	v_mfma_f32_16x16x32_bf16 v[24:27], v[70:73], v[82:85], v[24:27]
	v_cndmask_b32_e64 v66, v66, 0, s[22:23]
	v_cndmask_b32_e64 v68, v68, 0, s[28:29]
	v_cndmask_b32_e64 v69, v69, 0, s[36:37]
	v_mfma_f32_16x16x32_bf16 v[20:23], v[42:45], v[82:85], v[20:23]
	v_add_f32_e32 v41, v106, v41
	v_cvt_pk_bf16_f32 v102, v107, v111
	v_cvt_pk_bf16_f32 v103, v113, v106
	s_waitcnt lgkmcnt(0)
	v_mfma_f32_16x16x32_bf16 v[16:19], v[60:63], v[82:85], v[16:19]
	v_cvt_pk_bf16_f32 v104, v66, v117
	v_cvt_pk_bf16_f32 v105, v68, v69
	v_add_f32_e32 v41, v66, v41
	v_add_f32_e32 v41, v117, v41
	v_mfma_f32_16x16x32_bf16 v[28:31], v[98:101], v[102:105], v[28:31]
	v_add_f32_e32 v41, v68, v41
	v_add_f32_e32 v66, v69, v41
	v_fmac_f32_e32 v66, v40, v46
	v_mfma_f32_16x16x32_bf16 v[24:27], v[74:77], v[102:105], v[24:27]
	v_mfma_f32_16x16x32_bf16 v[20:23], v[56:59], v[102:105], v[20:23]
	v_mfma_f32_16x16x32_bf16 v[16:19], v[78:81], v[102:105], v[16:19]
	s_cbranch_scc0 .LBB0_625
